# MFMA-first head: no softmax VALU in the two steps behind the tile barrier, softmax_B spread over the remaining eight steps
# baseline (speedup 1.0000x reference)
; #define LAS __attribute__((address_space(3)))
; __device__ __forceinline__ void softmax_blk(f32x16& p0, f32x16& p1, f32x16& o0, f32x16& o1, float& mhat, float& lrun, u32x4 (&pf)[4], bool first) {
;     float r0 = max2_(p0[0], p0[1]), r1 = max2_(p1[0], p1[1]);
; #pragma unroll
;     for (int e = 2; e < 16; ++e) { r0 = max2_(r0, p0[e]); r1 = max2_(r1, p1[e]); }
;     const float rm = swap_max(max2_(r0, r1));
;     if (first || __any(rm - mhat > THR)) {
;         const float mn = first ? rm : fmaxf(rm, mhat); const float f = first ? 0.f : __builtin_amdgcn_exp2f(mhat - mn); mhat = mn; lrun *= f;
; #pragma unroll
;         for (int e = 0; e < 16; ++e) { o0[e] *= f; o1[e] *= f; }
;     }
;     float s0 = 0.f, s1 = 0.f;
; #pragma unroll
;     for (int e = 0; e < 16; ++e) { p0[e] = __builtin_amdgcn_exp2f(p0[e] - mhat); p1[e] = __builtin_amdgcn_exp2f(p1[e] - mhat); s0 += p0[e]; s1 += p1[e]; }
;     lrun += s0 + s1;
;     pf[0] = MLA_PACK(p0, 0); pf[1] = MLA_PACK(p0, 8); pf[2] = MLA_PACK(p1, 0); pf[3] = MLA_PACK(p1, 8);
; }
; __device__ __forceinline__ void pv_blk(const u32x4 (&pf)[4], f32x16& o0, f32x16& o1, LAS const unsigned char* vbase) {
; #pragma unroll
;     for (int ks = 0; ks < 4; ++ks) {
;         const bf16x8 p = __builtin_bit_cast(bf16x8, pf[ks]);
;         { const s16x4 lo = vtr(vbase + ks * 1024), hh = vtr(vbase + ks * 1024 + 512); const bf16x8 vf = {lo[0], lo[1], lo[2], lo[3], hh[0], hh[1], hh[2], hh[3]};
;           o0 = __builtin_amdgcn_mfma_f32_32x32x16_bf16(vf, p, o0, 0, 0, 0); }
;         { const s16x4 lo = vtr(vbase + 4096 + ks * 1024), hh = vtr(vbase + 4096 + ks * 1024 + 512); const bf16x8 vf = {lo[0], lo[1], lo[2], lo[3], hh[0], hh[1], hh[2], hh[3]};
;           o1 = __builtin_amdgcn_mfma_f32_32x32x16_bf16(vf, p, o1, 0, 0, 0); }
;     }
; }
; __device__ __forceinline__ void attn_unit(const bf16_t* Qh, const bf16_t* Kh, const bf16_t* Vh, bf16_t* Oh  , int S, int qb, LAS unsigned char* lds, int tid) {
;     ...
;         ka = GLD(u32x4, Kg + (size_t)tn * 768 + kc0); kb = GLD(u32x4, Kg + (size_t)tn * 768 + kc1); va = GLD(u32x4, Vg + (size_t)tn * 512 + tid);
;         u32x4 pf[4];
;         {
;             f32x16 p0 = {}, p1 = {};
; #pragma unroll
;             for (int s = 0; s < 6; ++s) {
;                 const bf16x8 a0 = *(const LAS bf16x8*)(lds + cur + kfo + s * 32), a1 = *(const LAS bf16x8*)(lds + cur + kfo + 32 * KPITCH + s * 32);
.Lmla_top:
	ds_read_b64_tr_b16 v[128:129], v158 offset:13312
	ds_read_b64_tr_b16 v[130:131], v158 offset:13824
	ds_read_b64_tr_b16 v[142:143], v158 offset:17408
	ds_read_b64_tr_b16 v[144:145], v158 offset:17920
	ds_read_b64_tr_b16 v[176:177], v158 offset:14336
	ds_read_b64_tr_b16 v[178:179], v158 offset:14848
	ds_read_b64_tr_b16 v[180:181], v158 offset:18432
	ds_read_b64_tr_b16 v[182:183], v158 offset:18944
	s_waitcnt lgkmcnt(4)
	v_mfma_f32_32x32x16_bf16 v[16:31], v[128:131], v[64:67], v[16:31]
	v_mfma_f32_32x32x16_bf16 v[0:15], v[142:145], v[64:67], v[0:15]
	ds_read_b64_tr_b16 v[128:129], v158 offset:15360
	ds_read_b64_tr_b16 v[130:131], v158 offset:15872
	ds_read_b64_tr_b16 v[142:143], v158 offset:19456
	ds_read_b64_tr_b16 v[144:145], v158 offset:19968
	global_load_dwordx4 v[218:221], v171, s[26:27]
	global_load_dwordx4 v[222:225], v184, s[26:27]
	global_load_dwordx4 v[226:229], v146, s[100:101]
	s_add_u32 s26, s26, 0x3000
	s_addc_u32 s27, s27, 0
	s_add_u32 s100, s100, 0x2000
	s_addc_u32 s101, s101, 0
	s_waitcnt lgkmcnt(4)
	v_mfma_f32_32x32x16_bf16 v[16:31], v[176:179], v[68:71], v[16:31]
	v_mfma_f32_32x32x16_bf16 v[0:15], v[180:183], v[68:71], v[0:15]
	ds_read_b64_tr_b16 v[176:177], v158 offset:16384
	ds_read_b64_tr_b16 v[178:179], v158 offset:16896
	ds_read_b64_tr_b16 v[180:181], v158 offset:20480
	ds_read_b64_tr_b16 v[182:183], v158 offset:20992
	s_waitcnt lgkmcnt(4)
	v_mfma_f32_32x32x16_bf16 v[16:31], v[128:131], v[72:75], v[16:31]
	v_mfma_f32_32x32x16_bf16 v[0:15], v[142:145], v[72:75], v[0:15]
	ds_read_b128 v[128:131], v155 offset:21504
	ds_read_b128 v[142:145], v155 offset:28160
	ds_read_b128 v[162:165], v135 offset:43008
	v_max3_f32 v248, v96, v97, v98
	v_max3_f32 v249, v112, v113, v114
	v_max3_f32 v248, v248, v99, v100
	v_max3_f32 v249, v249, v115, v116
	v_max3_f32 v248, v248, v101, v102
	v_max3_f32 v249, v249, v117, v118
	v_max3_f32 v248, v248, v103, v104
	v_max3_f32 v249, v249, v119, v120
	v_max3_f32 v248, v248, v105, v106
	v_max3_f32 v249, v249, v121, v122
	v_max3_f32 v248, v248, v107, v108
	v_max3_f32 v249, v249, v123, v124
	v_max3_f32 v248, v248, v109, v110
	v_max3_f32 v249, v249, v125, v126
	v_max3_f32 v248, v248, v111, v127
	v_max_f32_e32 v248, v248, v249
	v_mov_b32_e32 v251, v248
	s_waitcnt lgkmcnt(3)
	v_mfma_f32_32x32x16_bf16 v[16:31], v[176:179], v[76:79], v[16:31]
	v_mfma_f32_32x32x16_bf16 v[0:15], v[180:183], v[76:79], v[0:15]
	ds_read_b128 v[176:179], v155 offset:21536
	ds_read_b128 v[180:183], v155 offset:28192
	ds_read_b128 v[186:189], v135 offset:44032
	s_nop 1
	v_permlane32_swap_b32_e32 v248, v251
	v_max_f32_e32 v167, v248, v251
	v_cmp_lt_f32_e32 vcc, s72, v167
	s_cbranch_vccnz .Lmla_rescBo
.Lmla_rescBo_back:
	v_exp_f32_e32 v96, v96
	v_exp_f32_e32 v97, v97
	v_exp_f32_e32 v98, v98
	v_exp_f32_e32 v99, v99
	v_exp_f32_e32 v100, v100
	v_exp_f32_e32 v101, v101
	s_waitcnt lgkmcnt(3)
	v_mfma_f32_32x32x16_bf16 v[64:79], v[128:131], v[162:165], v[232:247]
	v_mfma_f32_32x32x16_bf16 v[80:95], v[142:145], v[162:165], v[232:247]
	ds_read_b128 v[128:131], v155 offset:21568
	ds_read_b128 v[142:145], v155 offset:28224
	ds_read_b128 v[162:165], v135 offset:45056
	v_exp_f32_e32 v102, v102
	v_exp_f32_e32 v103, v103
	v_add_f32_e32 v166, v96, v97
	v_add_f32_e32 v141, v141, v98
	v_add_f32_e32 v166, v166, v99
	v_cvt_pk_bf16_f32 v96, v96, v97
	v_cvt_pk_bf16_f32 v97, v98, v99
	v_exp_f32_e32 v104, v104
	v_exp_f32_e32 v105, v105
	v_exp_f32_e32 v106, v106
	v_exp_f32_e32 v107, v107
	s_waitcnt lgkmcnt(3)
	v_mfma_f32_32x32x16_bf16 v[64:79], v[176:179], v[186:189], v[64:79]
	v_mfma_f32_32x32x16_bf16 v[80:95], v[180:183], v[186:189], v[80:95]
	ds_read_b128 v[176:179], v155 offset:21600
	ds_read_b128 v[180:183], v155 offset:28256
	ds_read_b128 v[186:189], v135 offset:46080
	v_add_f32_e32 v141, v141, v100
	v_add_f32_e32 v166, v166, v101
	v_add_f32_e32 v141, v141, v102
	v_add_f32_e32 v166, v166, v103
	v_cvt_pk_bf16_f32 v98, v100, v101
	v_cvt_pk_bf16_f32 v99, v102, v103
	v_exp_f32_e32 v108, v108
	v_exp_f32_e32 v109, v109
	v_exp_f32_e32 v110, v110
	v_exp_f32_e32 v111, v111
	v_add_f32_e32 v141, v141, v104
	v_add_f32_e32 v166, v166, v105
	s_waitcnt lgkmcnt(3)
	v_mfma_f32_32x32x16_bf16 v[64:79], v[128:131], v[162:165], v[64:79]
	v_mfma_f32_32x32x16_bf16 v[80:95], v[142:145], v[162:165], v[80:95]
	ds_read_b128 v[128:131], v155 offset:21632
	ds_read_b128 v[142:145], v155 offset:28288
	ds_read_b128 v[162:165], v135 offset:47104
	v_add_f32_e32 v141, v141, v106
	v_add_f32_e32 v166, v166, v107
	v_cvt_pk_bf16_f32 v100, v104, v105
	v_cvt_pk_bf16_f32 v101, v106, v107
	v_exp_f32_e32 v112, v112
	v_exp_f32_e32 v113, v113
	v_exp_f32_e32 v114, v114
	v_exp_f32_e32 v115, v115
	v_add_f32_e32 v141, v141, v108
	v_add_f32_e32 v166, v166, v109
	v_add_f32_e32 v141, v141, v110
	v_add_f32_e32 v166, v166, v111
	v_cvt_pk_bf16_f32 v102, v108, v109
	s_waitcnt lgkmcnt(3)
	v_mfma_f32_32x32x16_bf16 v[64:79], v[176:179], v[186:189], v[64:79]
	v_mfma_f32_32x32x16_bf16 v[80:95], v[180:183], v[186:189], v[80:95]
	ds_read_b128 v[176:179], v155 offset:21664
	ds_read_b128 v[180:183], v155 offset:28320
	ds_read_b128 v[186:189], v135 offset:48128
	v_cvt_pk_bf16_f32 v103, v110, v111
	v_exp_f32_e32 v116, v116
	v_exp_f32_e32 v117, v117
	v_exp_f32_e32 v118, v118
	v_exp_f32_e32 v119, v119
	v_add_f32_e32 v141, v141, v112
	v_add_f32_e32 v166, v166, v113
	v_add_f32_e32 v141, v141, v114
	v_add_f32_e32 v166, v166, v115
	v_cvt_pk_bf16_f32 v104, v112, v113
	v_cvt_pk_bf16_f32 v105, v114, v115
	v_exp_f32_e32 v120, v120
	s_waitcnt lgkmcnt(3)
; #define LAS __attribute__((address_space(3)))
; __device__ __forceinline__ void softmax_blk(f32x16& p0, f32x16& p1, f32x16& o0, f32x16& o1, float& mhat, float& lrun, u32x4 (&pf)[4], bool first) {
;     float r0 = max2_(p0[0], p0[1]), r1 = max2_(p1[0], p1[1]);
; #pragma unroll
;     for (int e = 2; e < 16; ++e) { r0 = max2_(r0, p0[e]); r1 = max2_(r1, p1[e]); }
;     const float rm = swap_max(max2_(r0, r1));
;     if (first || __any(rm - mhat > THR)) {
;         const float mn = first ? rm : fmaxf(rm, mhat); const float f = first ? 0.f : __builtin_amdgcn_exp2f(mhat - mn); mhat = mn; lrun *= f;
; #pragma unroll
;         for (int e = 0; e < 16; ++e) { o0[e] *= f; o1[e] *= f; }
;     }
;     float s0 = 0.f, s1 = 0.f;
; #pragma unroll
;     for (int e = 0; e < 16; ++e) { p0[e] = __builtin_amdgcn_exp2f(p0[e] - mhat); p1[e] = __builtin_amdgcn_exp2f(p1[e] - mhat); s0 += p0[e]; s1 += p1[e]; }
;     lrun += s0 + s1;
;     pf[0] = MLA_PACK(p0, 0); pf[1] = MLA_PACK(p0, 8); pf[2] = MLA_PACK(p1, 0); pf[3] = MLA_PACK(p1, 8);
; }
; __device__ __forceinline__ void pv_blk(const u32x4 (&pf)[4], f32x16& o0, f32x16& o1, LAS const unsigned char* vbase) {
; #pragma unroll
;     for (int ks = 0; ks < 4; ++ks) {
;         const bf16x8 p = __builtin_bit_cast(bf16x8, pf[ks]);
;         { const s16x4 lo = vtr(vbase + ks * 1024), hh = vtr(vbase + ks * 1024 + 512); const bf16x8 vf = {lo[0], lo[1], lo[2], lo[3], hh[0], hh[1], hh[2], hh[3]};
;           o0 = __builtin_amdgcn_mfma_f32_32x32x16_bf16(vf, p, o0, 0, 0, 0); }
;         { const s16x4 lo = vtr(vbase + 4096 + ks * 1024), hh = vtr(vbase + 4096 + ks * 1024 + 512); const bf16x8 vf = {lo[0], lo[1], lo[2], lo[3], hh[0], hh[1], hh[2], hh[3]};
;           o1 = __builtin_amdgcn_mfma_f32_32x32x16_bf16(vf, p, o1, 0, 0, 0); }
;     }
; }
; __device__ __forceinline__ void attn_unit(const bf16_t* Qh, const bf16_t* Kh, const bf16_t* Vh, bf16_t* Oh  , int S, int qb, LAS unsigned char* lds, int tid) {
;     ...
;         ka = GLD(u32x4, Kg + (size_t)tn * 768 + kc0); kb = GLD(u32x4, Kg + (size_t)tn * 768 + kc1); va = GLD(u32x4, Vg + (size_t)tn * 512 + tid);
;         u32x4 pf[4];
;         {
;             f32x16 p0 = {}, p1 = {};
; #pragma unroll
;             for (int s = 0; s < 6; ++s) {
;                 const bf16x8 a0 = *(const LAS bf16x8*)(lds + cur + kfo + s * 32), a1 = *(const LAS bf16x8*)(lds + cur + kfo + 32 * KPITCH + s * 32);
	v_mfma_f32_32x32x16_bf16 v[64:79], v[128:131], v[162:165], v[64:79]
	v_mfma_f32_32x32x16_bf16 v[80:95], v[142:145], v[162:165], v[80:95]
	ds_read_b64_tr_b16 v[128:129], v158 offset:13312
	ds_read_b64_tr_b16 v[130:131], v158 offset:13824
	ds_read_b64_tr_b16 v[142:143], v158 offset:17408
	ds_read_b64_tr_b16 v[144:145], v158 offset:17920
	v_exp_f32_e32 v121, v121
	v_exp_f32_e32 v122, v122
	v_exp_f32_e32 v123, v123
	v_add_f32_e32 v141, v141, v116
	v_add_f32_e32 v166, v166, v117
	v_add_f32_e32 v141, v141, v118
	v_add_f32_e32 v166, v166, v119
	v_cvt_pk_bf16_f32 v106, v116, v117
	v_cvt_pk_bf16_f32 v107, v118, v119
	v_exp_f32_e32 v124, v124
	v_exp_f32_e32 v125, v125
	v_exp_f32_e32 v126, v126
	s_waitcnt lgkmcnt(4)
	v_mfma_f32_32x32x16_bf16 v[64:79], v[176:179], v[186:189], v[64:79]
	v_mfma_f32_32x32x16_bf16 v[80:95], v[180:183], v[186:189], v[80:95]
	ds_read_b64_tr_b16 v[176:177], v158 offset:14336
	ds_read_b64_tr_b16 v[178:179], v158 offset:14848
	ds_read_b64_tr_b16 v[180:181], v158 offset:18432
	ds_read_b64_tr_b16 v[182:183], v158 offset:18944
	v_exp_f32_e32 v127, v127
	v_add_f32_e32 v141, v141, v120
	v_add_f32_e32 v166, v166, v121
	v_add_f32_e32 v141, v141, v122
	v_add_f32_e32 v166, v166, v123
	v_cvt_pk_bf16_f32 v108, v120, v121
	v_cvt_pk_bf16_f32 v109, v122, v123
	v_add_f32_e32 v141, v141, v124
	v_add_f32_e32 v166, v166, v125
	v_add_f32_e32 v141, v141, v126
	v_add_f32_e32 v166, v166, v127
	v_cvt_pk_bf16_f32 v110, v124, v125
	v_cvt_pk_bf16_f32 v111, v126, v127
	v_add_f32_e32 v141, v141, v166
	s_waitcnt lgkmcnt(4)
	v_mfma_f32_32x32x16_bf16 v[48:63], v[128:131], v[96:99], v[48:63]
	v_mfma_f32_32x32x16_bf16 v[32:47], v[142:145], v[96:99], v[32:47]
	ds_read_b64_tr_b16 v[128:129], v158 offset:15360
	ds_read_b64_tr_b16 v[130:131], v158 offset:15872
	ds_read_b64_tr_b16 v[142:143], v158 offset:19456
	ds_read_b64_tr_b16 v[144:145], v158 offset:19968
	v_max3_f32 v248, v64, v65, v66
	v_max3_f32 v249, v80, v81, v82
	v_max3_f32 v248, v248, v67, v68
	v_max3_f32 v249, v249, v83, v84
	v_max3_f32 v248, v248, v69, v70
	v_max3_f32 v249, v249, v85, v86
	v_max3_f32 v248, v248, v71, v72
	v_max3_f32 v249, v249, v87, v88
	v_max3_f32 v248, v248, v73, v74
	v_max3_f32 v249, v249, v89, v90
	v_max3_f32 v248, v248, v75, v76
	v_max3_f32 v249, v249, v91, v92
	v_max3_f32 v248, v248, v77, v78
	v_max3_f32 v249, v249, v93, v94
	s_waitcnt lgkmcnt(4)
	v_mfma_f32_32x32x16_bf16 v[48:63], v[176:179], v[100:103], v[48:63]
	v_mfma_f32_32x32x16_bf16 v[32:47], v[180:183], v[100:103], v[32:47]
	ds_read_b64_tr_b16 v[176:177], v158 offset:16384
	ds_read_b64_tr_b16 v[178:179], v158 offset:16896
	ds_read_b64_tr_b16 v[180:181], v158 offset:20480
	ds_read_b64_tr_b16 v[182:183], v158 offset:20992
	v_max3_f32 v248, v248, v79, v95
	v_max_f32_e32 v248, v248, v249
	v_mov_b32_e32 v251, v248
	s_nop 1
	v_permlane32_swap_b32_e32 v248, v251
	v_max_f32_e32 v167, v248, v251
	v_cmp_lt_f32_e32 vcc, s72, v167
	s_cbranch_vccnz .Lmla_rescAo
.Lmla_rescAo_back:
	v_exp_f32_e32 v64, v64
	v_exp_f32_e32 v65, v65
	v_exp_f32_e32 v66, v66
	s_waitcnt lgkmcnt(4)
	v_mfma_f32_32x32x16_bf16 v[48:63], v[128:131], v[104:107], v[48:63]
	v_mfma_f32_32x32x16_bf16 v[32:47], v[142:145], v[104:107], v[32:47]
	ds_read_b128 v[128:131], v155 offset:21504
	ds_read_b128 v[142:145], v155 offset:28160
	ds_read_b128 v[162:165], v135 offset:49152
	v_exp_f32_e32 v67, v67
	v_exp_f32_e32 v68, v68
	v_exp_f32_e32 v69, v69
	v_exp_f32_e32 v70, v70
	v_exp_f32_e32 v71, v71
	v_add_f32_e32 v166, v64, v65
	v_add_f32_e32 v140, v140, v66
	v_add_f32_e32 v166, v166, v67
	s_waitcnt lgkmcnt(3)
	v_mfma_f32_32x32x16_bf16 v[48:63], v[176:179], v[108:111], v[48:63]
	v_mfma_f32_32x32x16_bf16 v[32:47], v[180:183], v[108:111], v[32:47]
	ds_read_b128 v[176:179], v155 offset:21536
	ds_read_b128 v[180:183], v155 offset:28192
	ds_read_b128 v[186:189], v135 offset:50176
	v_cvt_pk_bf16_f32 v64, v64, v65
	v_cvt_pk_bf16_f32 v65, v66, v67
	v_exp_f32_e32 v72, v72
	v_exp_f32_e32 v73, v73
	v_exp_f32_e32 v74, v74
	v_exp_f32_e32 v75, v75
	v_add_f32_e32 v140, v140, v68
	v_add_f32_e32 v166, v166, v69
	v_add_f32_e32 v140, v140, v70
	s_waitcnt lgkmcnt(3)
	v_mfma_f32_32x32x16_bf16 v[96:111], v[128:131], v[162:165], v[190:205]
	v_mfma_f32_32x32x16_bf16 v[112:127], v[142:145], v[162:165], v[190:205]
	ds_read_b128 v[128:131], v155 offset:21568
	ds_read_b128 v[142:145], v155 offset:28224
	ds_read_b128 v[162:165], v135 offset:51200
	v_add_f32_e32 v166, v166, v71
	v_cvt_pk_bf16_f32 v66, v68, v69
	v_cvt_pk_bf16_f32 v67, v70, v71
	v_exp_f32_e32 v76, v76
	v_exp_f32_e32 v77, v77
	v_exp_f32_e32 v78, v78
	v_exp_f32_e32 v79, v79
	v_add_f32_e32 v140, v140, v72
	v_add_f32_e32 v166, v166, v73
	s_waitcnt lgkmcnt(3)
	v_mfma_f32_32x32x16_bf16 v[96:111], v[176:179], v[186:189], v[96:111]
	v_mfma_f32_32x32x16_bf16 v[112:127], v[180:183], v[186:189], v[112:127]
	ds_read_b128 v[176:179], v155 offset:21600
	ds_read_b128 v[180:183], v155 offset:28256
	ds_read_b128 v[186:189], v135 offset:52224
	v_add_f32_e32 v140, v140, v74
	v_add_f32_e32 v166, v166, v75
	v_cvt_pk_bf16_f32 v68, v72, v73
	v_cvt_pk_bf16_f32 v69, v74, v75
	v_exp_f32_e32 v80, v80
	v_exp_f32_e32 v81, v81
	v_exp_f32_e32 v82, v82
	v_exp_f32_e32 v83, v83
	v_add_f32_e32 v140, v140, v76
	v_add_f32_e32 v166, v166, v77
	s_waitcnt lgkmcnt(3)
	v_mfma_f32_32x32x16_bf16 v[96:111], v[128:131], v[162:165], v[96:111]
	v_mfma_f32_32x32x16_bf16 v[112:127], v[142:145], v[162:165], v[112:127]
	ds_read_b128 v[128:131], v155 offset:21632
	ds_read_b128 v[142:145], v155 offset:28288
	ds_read_b128 v[162:165], v135 offset:53248
	v_add_f32_e32 v140, v140, v78
	v_add_f32_e32 v166, v166, v79
	v_cvt_pk_bf16_f32 v70, v76, v77
	v_cvt_pk_bf16_f32 v71, v78, v79
	v_exp_f32_e32 v84, v84
	v_exp_f32_e32 v85, v85
	v_exp_f32_e32 v86, v86
	v_exp_f32_e32 v87, v87
	v_add_f32_e32 v140, v140, v80
	s_waitcnt lgkmcnt(3)
; #define LAS __attribute__((address_space(3)))
; __device__ __forceinline__ void softmax_blk(f32x16& p0, f32x16& p1, f32x16& o0, f32x16& o1, float& mhat, float& lrun, u32x4 (&pf)[4], bool first) {
;     float r0 = max2_(p0[0], p0[1]), r1 = max2_(p1[0], p1[1]);
; #pragma unroll
;     for (int e = 2; e < 16; ++e) { r0 = max2_(r0, p0[e]); r1 = max2_(r1, p1[e]); }
;     const float rm = swap_max(max2_(r0, r1));
;     if (first || __any(rm - mhat > THR)) {
;         const float mn = first ? rm : fmaxf(rm, mhat); const float f = first ? 0.f : __builtin_amdgcn_exp2f(mhat - mn); mhat = mn; lrun *= f;
; #pragma unroll
;         for (int e = 0; e < 16; ++e) { o0[e] *= f; o1[e] *= f; }
;     }
;     float s0 = 0.f, s1 = 0.f;
; #pragma unroll
;     for (int e = 0; e < 16; ++e) { p0[e] = __builtin_amdgcn_exp2f(p0[e] - mhat); p1[e] = __builtin_amdgcn_exp2f(p1[e] - mhat); s0 += p0[e]; s1 += p1[e]; }
;     lrun += s0 + s1;
;     pf[0] = MLA_PACK(p0, 0); pf[1] = MLA_PACK(p0, 8); pf[2] = MLA_PACK(p1, 0); pf[3] = MLA_PACK(p1, 8);
; }
; __device__ __forceinline__ void pv_blk(const u32x4 (&pf)[4], f32x16& o0, f32x16& o1, LAS const unsigned char* vbase) {
; #pragma unroll
;     for (int ks = 0; ks < 4; ++ks) {
;         const bf16x8 p = __builtin_bit_cast(bf16x8, pf[ks]);
;         { const s16x4 lo = vtr(vbase + ks * 1024), hh = vtr(vbase + ks * 1024 + 512); const bf16x8 vf = {lo[0], lo[1], lo[2], lo[3], hh[0], hh[1], hh[2], hh[3]};
;           o0 = __builtin_amdgcn_mfma_f32_32x32x16_bf16(vf, p, o0, 0, 0, 0); }
;         { const s16x4 lo = vtr(vbase + 4096 + ks * 1024), hh = vtr(vbase + 4096 + ks * 1024 + 512); const bf16x8 vf = {lo[0], lo[1], lo[2], lo[3], hh[0], hh[1], hh[2], hh[3]};
;           o1 = __builtin_amdgcn_mfma_f32_32x32x16_bf16(vf, p, o1, 0, 0, 0); }
;     }
; }
; __device__ __forceinline__ void attn_unit(const bf16_t* Qh, const bf16_t* Kh, const bf16_t* Vh, bf16_t* Oh  , int S, int qb, LAS unsigned char* lds, int tid) {
;     ...
;     for (int t = 0; t < NT; ++t) {
;         const unsigned cur = (unsigned)(t & 1) * BUF, nxt = BUF - cur;
;         const int tn = t + 1 < NT ? t + 1 : t;
;         ka = GLD(u32x4, Kg + (size_t)tn * 768 + kc0); kb = GLD(u32x4, Kg + (size_t)tn * 768 + kc1); va = GLD(u32x4, Vg + (size_t)tn * 512 + tid);
;         u32x4 pf[4];
;         {
;             f32x16 p0 = {}, p1 = {};
; #pragma unroll
;             for (int s = 0; s < 6; ++s) {
	v_mfma_f32_32x32x16_bf16 v[96:111], v[176:179], v[186:189], v[96:111]
	v_mfma_f32_32x32x16_bf16 v[112:127], v[180:183], v[186:189], v[112:127]
	ds_read_b128 v[176:179], v155 offset:21664
	ds_read_b128 v[180:183], v155 offset:28320
	ds_read_b128 v[186:189], v135 offset:54272
	v_add_f32_e32 v166, v166, v81
	v_add_f32_e32 v140, v140, v82
	v_add_f32_e32 v166, v166, v83
	v_cvt_pk_bf16_f32 v72, v80, v81
	v_cvt_pk_bf16_f32 v73, v82, v83
	v_exp_f32_e32 v88, v88
	v_exp_f32_e32 v89, v89
	v_exp_f32_e32 v90, v90
	v_exp_f32_e32 v91, v91
	v_add_f32_e32 v140, v140, v84
	s_waitcnt vmcnt(0)
	ds_write_b128 v150, v[218:221]
	ds_write_b128 v156, v[222:225]
	ds_write_b128 v157, v[226:229] offset:34816
	s_waitcnt lgkmcnt(6)
	v_mfma_f32_32x32x16_bf16 v[96:111], v[128:131], v[162:165], v[96:111]
	v_mfma_f32_32x32x16_bf16 v[112:127], v[142:145], v[162:165], v[112:127]
	v_add_f32_e32 v166, v166, v85
	v_add_f32_e32 v140, v140, v86
	v_add_f32_e32 v166, v166, v87
	v_cvt_pk_bf16_f32 v74, v84, v85
	v_cvt_pk_bf16_f32 v75, v86, v87
	v_exp_f32_e32 v92, v92
	v_exp_f32_e32 v93, v93
	v_exp_f32_e32 v94, v94
	v_exp_f32_e32 v95, v95
	s_waitcnt lgkmcnt(3)
	v_mfma_f32_32x32x16_bf16 v[96:111], v[176:179], v[186:189], v[96:111]
	v_mfma_f32_32x32x16_bf16 v[112:127], v[180:183], v[186:189], v[112:127]
	v_add_f32_e32 v140, v140, v88
	v_add_f32_e32 v166, v166, v89
	v_add_f32_e32 v140, v140, v90
	v_add_f32_e32 v166, v166, v91
	v_cvt_pk_bf16_f32 v76, v88, v89
	v_cvt_pk_bf16_f32 v77, v90, v91
	v_add_f32_e32 v140, v140, v92
	v_add_f32_e32 v166, v166, v93
	v_add_f32_e32 v140, v140, v94
	v_add_f32_e32 v166, v166, v95
	v_cvt_pk_bf16_f32 v78, v92, v93
	v_cvt_pk_bf16_f32 v79, v94, v95
	v_add_f32_e32 v140, v140, v166
	s_waitcnt lgkmcnt(0)
	s_barrier
	s_add_i32 s1, s1, 1
	s_cmp_lg_u32 s1, s18
	s_cbranch_scc0 .Lmla_epi
	ds_read_b64_tr_b16 v[128:129], v158 offset:34816
	ds_read_b64_tr_b16 v[130:131], v158 offset:35328
	ds_read_b64_tr_b16 v[142:143], v158 offset:38912
	ds_read_b64_tr_b16 v[144:145], v158 offset:39424
	ds_read_b64_tr_b16 v[176:177], v158 offset:35840
	ds_read_b64_tr_b16 v[178:179], v158 offset:36352
	ds_read_b64_tr_b16 v[180:181], v158 offset:39936
	ds_read_b64_tr_b16 v[182:183], v158 offset:40448
	s_waitcnt lgkmcnt(4)
	v_mfma_f32_32x32x16_bf16 v[16:31], v[128:131], v[64:67], v[16:31]
	v_mfma_f32_32x32x16_bf16 v[0:15], v[142:145], v[64:67], v[0:15]
	ds_read_b64_tr_b16 v[128:129], v158 offset:36864
	ds_read_b64_tr_b16 v[130:131], v158 offset:37376
	ds_read_b64_tr_b16 v[142:143], v158 offset:40960
	ds_read_b64_tr_b16 v[144:145], v158 offset:41472
	global_load_dwordx4 v[218:221], v171, s[26:27]
	global_load_dwordx4 v[222:225], v184, s[26:27]
	global_load_dwordx4 v[226:229], v146, s[100:101]
	s_add_u32 s26, s26, 0x3000
	s_addc_u32 s27, s27, 0
	s_add_u32 s100, s100, 0x2000
	s_addc_u32 s101, s101, 0
	s_waitcnt lgkmcnt(4)
	v_mfma_f32_32x32x16_bf16 v[16:31], v[176:179], v[68:71], v[16:31]
	v_mfma_f32_32x32x16_bf16 v[0:15], v[180:183], v[68:71], v[0:15]
	ds_read_b64_tr_b16 v[176:177], v158 offset:37888
	ds_read_b64_tr_b16 v[178:179], v158 offset:38400
	ds_read_b64_tr_b16 v[180:181], v158 offset:41984
	ds_read_b64_tr_b16 v[182:183], v158 offset:42496
	s_waitcnt lgkmcnt(4)
	v_mfma_f32_32x32x16_bf16 v[16:31], v[128:131], v[72:75], v[16:31]
	v_mfma_f32_32x32x16_bf16 v[0:15], v[142:145], v[72:75], v[0:15]
	ds_read_b128 v[128:131], v155
	ds_read_b128 v[142:145], v155 offset:6656
	ds_read_b128 v[162:165], v135 offset:43008
	v_max3_f32 v248, v96, v97, v98
	v_max3_f32 v249, v112, v113, v114
	v_max3_f32 v248, v248, v99, v100
	v_max3_f32 v249, v249, v115, v116
	v_max3_f32 v248, v248, v101, v102
	v_max3_f32 v249, v249, v117, v118
	v_max3_f32 v248, v248, v103, v104
	v_max3_f32 v249, v249, v119, v120
	v_max3_f32 v248, v248, v105, v106
	v_max3_f32 v249, v249, v121, v122
	v_max3_f32 v248, v248, v107, v108
	v_max3_f32 v249, v249, v123, v124
	v_max3_f32 v248, v248, v109, v110
	v_max3_f32 v249, v249, v125, v126
	v_max3_f32 v248, v248, v111, v127
	v_max_f32_e32 v248, v248, v249
	v_mov_b32_e32 v251, v248
	s_waitcnt lgkmcnt(3)
	v_mfma_f32_32x32x16_bf16 v[16:31], v[176:179], v[76:79], v[16:31]
	v_mfma_f32_32x32x16_bf16 v[0:15], v[180:183], v[76:79], v[0:15]
	ds_read_b128 v[176:179], v155 offset:32
	ds_read_b128 v[180:183], v155 offset:6688
	ds_read_b128 v[186:189], v135 offset:44032
	s_nop 1
	v_permlane32_swap_b32_e32 v248, v251
	v_max_f32_e32 v167, v248, v251
	v_cmp_lt_f32_e32 vcc, s72, v167
	s_cbranch_vccnz .Lmla_rescBv
; #define LAS __attribute__((address_space(3)))
; __device__ __forceinline__ void softmax_blk(f32x16& p0, f32x16& p1, f32x16& o0, f32x16& o1, float& mhat, float& lrun, u32x4 (&pf)[4], bool first) {
;     float r0 = max2_(p0[0], p0[1]), r1 = max2_(p1[0], p1[1]);
; #pragma unroll
;     for (int e = 2; e < 16; ++e) { r0 = max2_(r0, p0[e]); r1 = max2_(r1, p1[e]); }
;     const float rm = swap_max(max2_(r0, r1));
;     if (first || __any(rm - mhat > THR)) {
;         const float mn = first ? rm : fmaxf(rm, mhat); const float f = first ? 0.f : __builtin_amdgcn_exp2f(mhat - mn); mhat = mn; lrun *= f;
; #pragma unroll
;         for (int e = 0; e < 16; ++e) { o0[e] *= f; o1[e] *= f; }
;     }
;     float s0 = 0.f, s1 = 0.f;
; #pragma unroll
;     for (int e = 0; e < 16; ++e) { p0[e] = __builtin_amdgcn_exp2f(p0[e] - mhat); p1[e] = __builtin_amdgcn_exp2f(p1[e] - mhat); s0 += p0[e]; s1 += p1[e]; }
;     lrun += s0 + s1;
;     pf[0] = MLA_PACK(p0, 0); pf[1] = MLA_PACK(p0, 8); pf[2] = MLA_PACK(p1, 0); pf[3] = MLA_PACK(p1, 8);
; }
; __device__ __forceinline__ void pv_blk(const u32x4 (&pf)[4], f32x16& o0, f32x16& o1, LAS const unsigned char* vbase) {
; #pragma unroll
;     for (int ks = 0; ks < 4; ++ks) {
;         const bf16x8 p = __builtin_bit_cast(bf16x8, pf[ks]);
;         { const s16x4 lo = vtr(vbase + ks * 1024), hh = vtr(vbase + ks * 1024 + 512); const bf16x8 vf = {lo[0], lo[1], lo[2], lo[3], hh[0], hh[1], hh[2], hh[3]};
;           o0 = __builtin_amdgcn_mfma_f32_32x32x16_bf16(vf, p, o0, 0, 0, 0); }
;         { const s16x4 lo = vtr(vbase + 4096 + ks * 1024), hh = vtr(vbase + 4096 + ks * 1024 + 512); const bf16x8 vf = {lo[0], lo[1], lo[2], lo[3], hh[0], hh[1], hh[2], hh[3]};
;           o1 = __builtin_amdgcn_mfma_f32_32x32x16_bf16(vf, p, o1, 0, 0, 0); }
;     }
; }
; __device__ __forceinline__ void attn_unit(const bf16_t* Qh, const bf16_t* Kh, const bf16_t* Vh, bf16_t* Oh  , int S, int qb, LAS unsigned char* lds, int tid) {
;     ...
;         ka = GLD(u32x4, Kg + (size_t)tn * 768 + kc0); kb = GLD(u32x4, Kg + (size_t)tn * 768 + kc1); va = GLD(u32x4, Vg + (size_t)tn * 512 + tid);
;         u32x4 pf[4];
;         {
;             f32x16 p0 = {}, p1 = {};
; #pragma unroll
;             for (int s = 0; s < 6; ++s) {
;                 const bf16x8 a0 = *(const LAS bf16x8*)(lds + cur + kfo + s * 32), a1 = *(const LAS bf16x8*)(lds + cur + kfo + 32 * KPITCH + s * 32);
.Lmla_rescBv_back:
	v_exp_f32_e32 v96, v96
	v_exp_f32_e32 v97, v97
	v_exp_f32_e32 v98, v98
	v_exp_f32_e32 v99, v99
	v_exp_f32_e32 v100, v100
	v_exp_f32_e32 v101, v101
	s_waitcnt lgkmcnt(3)
	v_mfma_f32_32x32x16_bf16 v[64:79], v[128:131], v[162:165], v[232:247]
	v_mfma_f32_32x32x16_bf16 v[80:95], v[142:145], v[162:165], v[232:247]
	ds_read_b128 v[128:131], v155 offset:64
	ds_read_b128 v[142:145], v155 offset:6720
	ds_read_b128 v[162:165], v135 offset:45056
	v_exp_f32_e32 v102, v102
	v_exp_f32_e32 v103, v103
	v_add_f32_e32 v166, v96, v97
	v_add_f32_e32 v141, v141, v98
	v_add_f32_e32 v166, v166, v99
	v_cvt_pk_bf16_f32 v96, v96, v97
	v_cvt_pk_bf16_f32 v97, v98, v99
	v_exp_f32_e32 v104, v104
	v_exp_f32_e32 v105, v105
	v_exp_f32_e32 v106, v106
	v_exp_f32_e32 v107, v107
	s_waitcnt lgkmcnt(3)
	v_mfma_f32_32x32x16_bf16 v[64:79], v[176:179], v[186:189], v[64:79]
	v_mfma_f32_32x32x16_bf16 v[80:95], v[180:183], v[186:189], v[80:95]
	ds_read_b128 v[176:179], v155 offset:96
	ds_read_b128 v[180:183], v155 offset:6752
	ds_read_b128 v[186:189], v135 offset:46080
	v_add_f32_e32 v141, v141, v100
	v_add_f32_e32 v166, v166, v101
	v_add_f32_e32 v141, v141, v102
	v_add_f32_e32 v166, v166, v103
	v_cvt_pk_bf16_f32 v98, v100, v101
	v_cvt_pk_bf16_f32 v99, v102, v103
	v_exp_f32_e32 v108, v108
	v_exp_f32_e32 v109, v109
	v_exp_f32_e32 v110, v110
	v_exp_f32_e32 v111, v111
	v_add_f32_e32 v141, v141, v104
	v_add_f32_e32 v166, v166, v105
	s_waitcnt lgkmcnt(3)
	v_mfma_f32_32x32x16_bf16 v[64:79], v[128:131], v[162:165], v[64:79]
	v_mfma_f32_32x32x16_bf16 v[80:95], v[142:145], v[162:165], v[80:95]
	ds_read_b128 v[128:131], v155 offset:128
	ds_read_b128 v[142:145], v155 offset:6784
	ds_read_b128 v[162:165], v135 offset:47104
	v_add_f32_e32 v141, v141, v106
	v_add_f32_e32 v166, v166, v107
	v_cvt_pk_bf16_f32 v100, v104, v105
	v_cvt_pk_bf16_f32 v101, v106, v107
	v_exp_f32_e32 v112, v112
	v_exp_f32_e32 v113, v113
	v_exp_f32_e32 v114, v114
	v_exp_f32_e32 v115, v115
	v_add_f32_e32 v141, v141, v108
	v_add_f32_e32 v166, v166, v109
	v_add_f32_e32 v141, v141, v110
	v_add_f32_e32 v166, v166, v111
	v_cvt_pk_bf16_f32 v102, v108, v109
	s_waitcnt lgkmcnt(3)
	v_mfma_f32_32x32x16_bf16 v[64:79], v[176:179], v[186:189], v[64:79]
	v_mfma_f32_32x32x16_bf16 v[80:95], v[180:183], v[186:189], v[80:95]
	ds_read_b128 v[176:179], v155 offset:160
	ds_read_b128 v[180:183], v155 offset:6816
	ds_read_b128 v[186:189], v135 offset:48128
	v_cvt_pk_bf16_f32 v103, v110, v111
	v_exp_f32_e32 v116, v116
	v_exp_f32_e32 v117, v117
	v_exp_f32_e32 v118, v118
	v_exp_f32_e32 v119, v119
	v_add_f32_e32 v141, v141, v112
	v_add_f32_e32 v166, v166, v113
	v_add_f32_e32 v141, v141, v114
	v_add_f32_e32 v166, v166, v115
	v_cvt_pk_bf16_f32 v104, v112, v113
	v_cvt_pk_bf16_f32 v105, v114, v115
	v_exp_f32_e32 v120, v120
	s_waitcnt lgkmcnt(3)
	v_mfma_f32_32x32x16_bf16 v[64:79], v[128:131], v[162:165], v[64:79]
	v_mfma_f32_32x32x16_bf16 v[80:95], v[142:145], v[162:165], v[80:95]
	ds_read_b64_tr_b16 v[128:129], v158 offset:34816
	ds_read_b64_tr_b16 v[130:131], v158 offset:35328
	ds_read_b64_tr_b16 v[142:143], v158 offset:38912
	ds_read_b64_tr_b16 v[144:145], v158 offset:39424
	v_exp_f32_e32 v121, v121
	v_exp_f32_e32 v122, v122
	v_exp_f32_e32 v123, v123
	v_add_f32_e32 v141, v141, v116
	v_add_f32_e32 v166, v166, v117
	v_add_f32_e32 v141, v141, v118
	v_add_f32_e32 v166, v166, v119
	v_cvt_pk_bf16_f32 v106, v116, v117
	v_cvt_pk_bf16_f32 v107, v118, v119
	v_exp_f32_e32 v124, v124
	v_exp_f32_e32 v125, v125
	v_exp_f32_e32 v126, v126
	s_waitcnt lgkmcnt(4)
	v_mfma_f32_32x32x16_bf16 v[64:79], v[176:179], v[186:189], v[64:79]
	v_mfma_f32_32x32x16_bf16 v[80:95], v[180:183], v[186:189], v[80:95]
	ds_read_b64_tr_b16 v[176:177], v158 offset:35840
	ds_read_b64_tr_b16 v[178:179], v158 offset:36352
	ds_read_b64_tr_b16 v[180:181], v158 offset:39936
	ds_read_b64_tr_b16 v[182:183], v158 offset:40448
	v_exp_f32_e32 v127, v127
	v_add_f32_e32 v141, v141, v120
	v_add_f32_e32 v166, v166, v121
	v_add_f32_e32 v141, v141, v122
	v_add_f32_e32 v166, v166, v123
	v_cvt_pk_bf16_f32 v108, v120, v121
	v_cvt_pk_bf16_f32 v109, v122, v123
	v_add_f32_e32 v141, v141, v124
	v_add_f32_e32 v166, v166, v125
	v_add_f32_e32 v141, v141, v126
	v_add_f32_e32 v166, v166, v127
	v_cvt_pk_bf16_f32 v110, v124, v125
	v_cvt_pk_bf16_f32 v111, v126, v127
	v_add_f32_e32 v141, v141, v166
	s_waitcnt lgkmcnt(4)
	v_mfma_f32_32x32x16_bf16 v[48:63], v[128:131], v[96:99], v[48:63]
	v_mfma_f32_32x32x16_bf16 v[32:47], v[142:145], v[96:99], v[32:47]
	ds_read_b64_tr_b16 v[128:129], v158 offset:36864
	ds_read_b64_tr_b16 v[130:131], v158 offset:37376
	ds_read_b64_tr_b16 v[142:143], v158 offset:40960
	ds_read_b64_tr_b16 v[144:145], v158 offset:41472
	v_max3_f32 v248, v64, v65, v66
	v_max3_f32 v249, v80, v81, v82
	v_max3_f32 v248, v248, v67, v68
	v_max3_f32 v249, v249, v83, v84
	v_max3_f32 v248, v248, v69, v70
	v_max3_f32 v249, v249, v85, v86
	v_max3_f32 v248, v248, v71, v72
	v_max3_f32 v249, v249, v87, v88
	v_max3_f32 v248, v248, v73, v74
	v_max3_f32 v249, v249, v89, v90
	v_max3_f32 v248, v248, v75, v76
	v_max3_f32 v249, v249, v91, v92
	v_max3_f32 v248, v248, v77, v78
	v_max3_f32 v249, v249, v93, v94
	s_waitcnt lgkmcnt(4)
	v_mfma_f32_32x32x16_bf16 v[48:63], v[176:179], v[100:103], v[48:63]
	v_mfma_f32_32x32x16_bf16 v[32:47], v[180:183], v[100:103], v[32:47]
	ds_read_b64_tr_b16 v[176:177], v158 offset:37888
	ds_read_b64_tr_b16 v[178:179], v158 offset:38400
	ds_read_b64_tr_b16 v[180:181], v158 offset:41984
	ds_read_b64_tr_b16 v[182:183], v158 offset:42496
	v_max3_f32 v248, v248, v79, v95
	v_max_f32_e32 v248, v248, v249
	v_mov_b32_e32 v251, v248
	s_nop 1
	v_permlane32_swap_b32_e32 v248, v251
	v_max_f32_e32 v167, v248, v251
	v_cmp_lt_f32_e32 vcc, s72, v167
	s_cbranch_vccnz .Lmla_rescAe
